# gMLP units: V^T fragment LDS reads of the spatial-mixing MFMA phase issued up to 12 reads ahead into private spare registers, lgkmcnt waits recomputed (on v85)
# speedup vs baseline: 1.0013x; 1.0013x over previous
; #define LAS __attribute__((address_space(3)))
; __device__ __forceinline__ void gmlp_unit(const bf16* proj, unsigned char* ws, LAS unsigned char* lds, int gu) {
;     ...
;     const int gb = gu >> 3, h = gu & 7, tok0 = gb * 128, fr = lane & 15, fq = lane >> 4;
;     LAS unsigned char* VN = lds;
;     const int c = tid & 15, r0 = tid >> 4;
;     v4u raw[4]; f32x2 stv[4];
;     tile_ld(raw, proj, tok0, C_VG + h * 128, tid);
; #pragma unroll
;     for (int p = 0; p < 4; ++p) stv[p] = *(const f32x2*)(lnstat + 2 * (tok0 + r0 + 32 * p));
;     const f32x4 g0 = *(const f32x4*)(par + PAR_GV + h * 128 + 8 * c), g1 = *(const f32x4*)(par + PAR_GV + h * 128 + 8 * c + 4);
;     const f32x4 b0 = *(const f32x4*)(par + PAR_BV + h * 128 + 8 * c), b1 = *(const f32x4*)(par + PAR_BV + h * 128 + 8 * c + 4);
;     bf16x8 wf[4];
; #pragma unroll
;     for (int s = 0; s < 4; ++s) wf[s] = *(const bf16x8*)(wsp + ((size_t)(h * 128 + 16 * wave + fr) * 128 + 32 * s + 8 * fq));
;     const int tok = tok0 + 16 * wave + fr; const float bsp = par[PAR_BSP + h * 128 + 16 * wave + fr];
;     const bf16* urow = proj + (size_t)tok * INW + C_U + h * 128 + 4 * fq; bf16* orow = mix + (size_t)tok * D + 1024 + h * 128 + 4 * fq;
;     v2u uw[8];
; #pragma unroll
;     for (int ct = 0; ct < 8; ++ct) uw[ct] = *(const v2u*)(urow + 16 * ct);
;     __syncthreads();
; #pragma unroll
;     for (int p = 0; p < 4; ++p) {
;         const float mu = stv[p][0] * (1.0f / 1024.0f), var = fmaxf(stv[p][1] * (1.0f / 1024.0f) - mu * mu, 0.f), rstd = 1.0f / sqrtf(var + pg8::EPSN);
.LBB0_600:
	s_add_i32 s0, s68, 0xfffffe00
	v_mov_b32_e32 v41, v160
	s_lshl_b32 s1, s0, 4
	s_and_b32 s4, s1, 0x3f80
	v_ashrrev_i32_e32 v76, 4, v41
	v_add_u32_e32 v10, s4, v76
	v_lshlrev_b32_e32 v0, 1, v10
	s_waitcnt lgkmcnt(0)
	v_ashrrev_i32_e32 v1, 31, v0
	v_lshl_add_u64 v[0:1], v[0:1], 2, s[28:29]
	global_load_dwordx2 v[8:9], v[0:1], off
	s_lshl_b32 s0, s0, 7
	s_and_b32 s13, s0, 0x380
	s_add_i32 s50, s13, 0xa00
	global_load_dwordx2 v[70:71], v[0:1], off offset:256
	global_load_dwordx2 v[72:73], v[0:1], off offset:512
	global_load_dwordx2 v[58:59], v[0:1], off offset:768
	s_lshl_b32 s0, s50, 1
	v_lshlrev_b32_e32 v2, 4, v41
	s_add_u32 s0, s26, s0
	v_and_b32_e32 v162, 0xf0, v2
	s_addc_u32 s1, s27, 0
	s_lshl_b32 s44, s13, 2
	v_lshl_add_u64 v[6:7], s[0:1], 0, v[162:163]
	s_add_u32 s0, s47, s44
	v_and_b32_e32 v78, 15, v41
	v_add_u32_e32 v11, 32, v10
	v_add_u32_e32 v12, 64, v10
	v_add_u32_e32 v15, 0x60, v10
	v_mad_i64_i32 v[0:1], s[2:3], v10, s60, v[6:7]
	s_addc_u32 s1, s53, 0
	v_lshlrev_b32_e32 v14, 5, v78
	v_mad_i64_i32 v[10:11], s[2:3], v11, s60, v[6:7]
	v_mad_i64_i32 v[12:13], s[2:3], v12, s60, v[6:7]
	v_mad_i64_i32 v[6:7], s[2:3], v15, s60, v[6:7]
	global_load_dwordx4 v[62:65], v[0:1], off
	global_load_dwordx4 v[66:69], v[10:11], off
	global_load_dwordx4 v[36:39], v[12:13], off
	global_load_dwordx4 v[32:35], v[6:7], off
	global_load_dwordx4 v[16:19], v14, s[0:1] offset:16
	global_load_dwordx4 v[28:31], v14, s[0:1]
	s_add_u32 s0, s58, s44
	s_addc_u32 s1, s59, 0
	global_load_dwordx4 v[20:23], v14, s[0:1] offset:16
	global_load_dwordx4 v[24:27], v14, s[0:1]
	v_readfirstlane_b32 s5, v41
	s_ashr_i32 s2, s5, 2
	s_and_b32 s0, s2, -16
	s_add_i32 s2, s0, s4
	v_or_b32_e32 v40, s2, v78
	s_add_i32 s1, s0, s13
	s_add_i32 s0, s0, s50
	v_or_b32_e32 v0, s1, v78
	v_or_b32_e32 v6, s0, v78
	v_mov_b64_e32 v[4:5], s[26:27]
	v_ashrrev_i32_e32 v1, 31, v0
	v_bfe_u32 v60, v41, 4, 2
	s_lshl_b32 s44, s13, 1
	v_mad_i64_i32 v[4:5], s[0:1], v40, s60, v[4:5]
	v_lshlrev_b64 v[0:1], 8, v[0:1]
	v_mov_b32_e32 v3, v163
	v_lshlrev_b32_e32 v2, 4, v60
	v_lshlrev_b32_e32 v162, 3, v60
	v_ashrrev_i32_e32 v7, 31, v6
	v_lshl_add_u64 v[4:5], v[4:5], 0, s[44:45]
	v_lshl_add_u64 v[0:1], s[42:43], 0, v[0:1]
	v_lshl_add_u64 v[6:7], v[6:7], 2, s[40:41]
	v_lshl_add_u64 v[4:5], v[4:5], 0, v[162:163]
	v_lshl_add_u64 v[10:11], v[0:1], 0, v[2:3]
	global_load_dword v61, v[6:7], off
	global_load_dwordx2 v[56:57], v[4:5], off offset:3072
	global_load_dwordx2 v[54:55], v[4:5], off offset:3104
	global_load_dwordx2 v[52:53], v[4:5], off offset:3136
	global_load_dwordx2 v[50:51], v[4:5], off offset:3168
	global_load_dwordx2 v[48:49], v[4:5], off offset:3200
	global_load_dwordx2 v[46:47], v[4:5], off offset:3232
	global_load_dwordx2 v[44:45], v[4:5], off offset:3264
	global_load_dwordx2 v[42:43], v[4:5], off offset:3296
	global_load_dwordx4 v[0:3], v[10:11], off
	s_nop 0
	global_load_dwordx4 v[4:7], v[10:11], off offset:64
	v_lshlrev_b32_e32 v78, 4, v78
	v_mul_lo_u32 v76, v76, s62
	v_add3_u32 v76, 0, v78, v76
	v_lshlrev_b32_e32 v77, 3, v41
	s_waitcnt vmcnt(22)
	v_pk_mul_f32 v[74:75], v[8:9], s[46:47] op_sel_hi:[1,0]
	s_nop 0
	v_fma_f32 v8, -v74, v74, v75
	v_max_f32_e32 v8, 0, v8
	v_add_f32_e32 v8, 0x358637bd, v8
	v_mul_f32_e32 v9, 0x4f800000, v8
	v_cmp_gt_f32_e32 vcc, s61, v8
	s_waitcnt vmcnt(21)
	v_pk_mul_f32 v[70:71], v[70:71], s[46:47] op_sel_hi:[1,0]
	s_waitcnt vmcnt(19)
	v_pk_mul_f32 v[58:59], v[58:59], s[46:47] op_sel_hi:[1,0]
	v_cndmask_b32_e32 v75, v8, v9, vcc
	v_sqrt_f32_e32 v79, v75
	v_fma_f32 v71, -v70, v70, v71
	v_max_f32_e32 v71, 0, v71
	v_add_f32_e32 v71, 0x358637bd, v71
	v_add_u32_e32 v80, -1, v79
	v_fma_f32 v81, -v80, v79, v75
	v_cmp_ge_f32_e64 s[2:3], 0, v81
	v_add_u32_e32 v81, 1, v79
	global_load_dwordx4 v[12:15], v[10:11], off offset:128
	s_nop 0
	global_load_dwordx4 v[8:11], v[10:11], off offset:192
	v_cndmask_b32_e64 v80, v79, v80, s[2:3]
	v_fma_f32 v79, -v81, v79, v75
	v_cmp_lt_f32_e64 s[2:3], 0, v79
	s_barrier
	s_nop 0
	v_cndmask_b32_e64 v79, v80, v81, s[2:3]
	v_mul_f32_e32 v80, 0x37800000, v79
	v_cndmask_b32_e32 v79, v79, v80, vcc
	v_cmp_class_f32_e32 vcc, v75, v166
	v_fma_f32 v59, -v58, v58, v59
	s_nop 0
	v_cndmask_b32_e32 v75, v79, v75, vcc
	v_div_scale_f32 v79, s[0:1], v75, v75, 1.0
	v_rcp_f32_e32 v80, v79
	v_max_f32_e32 v59, 0, v59
	v_add_f32_e32 v59, 0x358637bd, v59
	v_fma_f32 v81, -v79, v80, 1.0
	v_fmac_f32_e32 v80, v81, v80
	v_div_scale_f32 v81, vcc, 1.0, v75, 1.0
	v_mul_f32_e32 v82, v81, v80
	v_fma_f32 v83, -v79, v82, v81
	v_fmac_f32_e32 v82, v83, v80
	v_fma_f32 v79, -v79, v82, v81
	v_div_fmas_f32 v79, v79, v80, v82
	v_div_fixup_f32 v75, v79, v75, 1.0
	s_waitcnt vmcnt(20)
	v_lshlrev_b32_e32 v79, 16, v62
	v_and_b32_e32 v62, 0xffff0000, v62
	v_lshlrev_b32_e32 v80, 16, v63
	v_and_b32_e32 v63, 0xffff0000, v63
	v_lshlrev_b32_e32 v81, 16, v64
	v_and_b32_e32 v64, 0xffff0000, v64
	v_lshlrev_b32_e32 v82, 16, v65
	v_and_b32_e32 v65, 0xffff0000, v65
	v_sub_f32_e32 v79, v79, v74
	v_sub_f32_e32 v81, v81, v74
	v_sub_f32_e32 v62, v62, v74
	v_sub_f32_e32 v64, v64, v74
	v_sub_f32_e32 v80, v80, v74
	v_sub_f32_e32 v82, v82, v74
	v_sub_f32_e32 v63, v63, v74
	v_sub_f32_e32 v65, v65, v74
	v_mul_f32_e32 v74, 0x4f800000, v71
	v_cmp_gt_f32_e32 vcc, s61, v71
	v_mul_f32_e32 v79, v79, v75
	v_mul_f32_e32 v62, v62, v75
	v_cndmask_b32_e32 v71, v71, v74, vcc
	v_sqrt_f32_e32 v74, v71
	s_waitcnt vmcnt(13)
; #define LAS __attribute__((address_space(3)))
; __device__ __forceinline__ unsigned pk2(float lo, float hi) { return pg8::cvt_pk_bf16(lo, hi); }
; __device__ __forceinline__ void gmlp_unit(const bf16* proj, unsigned char* ws, LAS unsigned char* lds, int gu) {
;     ...
;     for (int p = 0; p < 4; ++p) {
;         const float mu = stv[p][0] * (1.0f / 1024.0f), var = fmaxf(stv[p][1] * (1.0f / 1024.0f) - mu * mu, 0.f), rstd = 1.0f / sqrtf(var + pg8::EPSN);
;         float v[8];
;         v[0] = bflo(raw[p].x); v[1] = bfhi(raw[p].x); v[2] = bflo(raw[p].y); v[3] = bfhi(raw[p].y); v[4] = bflo(raw[p].z); v[5] = bfhi(raw[p].z); v[6] = bflo(raw[p].w); v[7] = bfhi(raw[p].w);
; #pragma unroll
;         for (int e = 0; e < 4; ++e) { v[e] = (v[e] - mu) * rstd * g0[e] + b0[e]; v[4 + e] = (v[4 + e] - mu) * rstd * g1[e] + b1[e]; }
;         v4u o; o.x = pk2(v[0], v[1]); o.y = pk2(v[2], v[3]); o.z = pk2(v[4], v[5]); o.w = pk2(v[6], v[7]);
;         *(LAS v4u*)(VN + (r0 + 32 * p) * V_STRIDE + c * 16) = o;
;     }
;     __syncthreads();
	v_fma_f32 v79, v28, v79, v24
	v_mul_f32_e32 v81, v81, v75
	v_fma_f32 v62, v29, v62, v25
	v_mul_f32_e32 v64, v64, v75
	v_mul_f32_e32 v80, v80, v75
	v_mul_f32_e32 v82, v82, v75
	v_mul_f32_e32 v63, v63, v75
	v_mul_f32_e32 v65, v65, v75
	v_add_u32_e32 v75, -1, v74
	v_cvt_pk_bf16_f32 v62, v79, v62
	v_fma_f32 v79, -v75, v74, v71
	v_cmp_ge_f32_e64 s[2:3], 0, v79
	v_add_u32_e32 v79, 1, v74
	v_fma_f32 v64, v17, v64, v21
	v_cndmask_b32_e64 v75, v74, v75, s[2:3]
	v_fma_f32 v74, -v79, v74, v71
	v_cmp_lt_f32_e64 s[2:3], 0, v74
	v_fma_f32 v63, v31, v63, v27
	v_fma_f32 v65, v19, v65, v23
	v_cndmask_b32_e64 v74, v75, v79, s[2:3]
	v_mul_f32_e32 v75, 0x37800000, v74
	v_cndmask_b32_e32 v74, v74, v75, vcc
	v_cmp_class_f32_e32 vcc, v71, v166
	v_fma_f32 v81, v16, v81, v20
	v_fma_f32 v80, v30, v80, v26
	v_cndmask_b32_e32 v71, v74, v71, vcc
	v_div_scale_f32 v74, s[0:1], v71, v71, 1.0
	v_rcp_f32_e32 v75, v74
	v_fma_f32 v82, v18, v82, v22
	v_cvt_pk_bf16_f32 v63, v80, v63
	v_cvt_pk_bf16_f32 v64, v81, v64
	v_cvt_pk_bf16_f32 v65, v82, v65
	ds_write_b128 v76, v[62:65]
	v_fma_f32 v62, -v74, v75, 1.0
	v_fmac_f32_e32 v75, v62, v75
	v_div_scale_f32 v62, vcc, 1.0, v71, 1.0
	v_mul_f32_e32 v63, v62, v75
	v_fma_f32 v64, -v74, v63, v62
	v_fmac_f32_e32 v63, v64, v75
	v_fma_f32 v62, -v74, v63, v62
	v_div_fmas_f32 v62, v62, v75, v63
	v_lshlrev_b32_e32 v63, 16, v66
	v_and_b32_e32 v64, 0xffff0000, v66
	v_lshlrev_b32_e32 v65, 16, v67
	v_and_b32_e32 v66, 0xffff0000, v67
	v_lshlrev_b32_e32 v67, 16, v68
	v_div_fixup_f32 v62, v62, v71, 1.0
	v_sub_f32_e32 v67, v67, v70
	v_and_b32_e32 v68, 0xffff0000, v68
	v_mul_f32_e32 v67, v67, v62
	v_fma_f32 v74, v16, v67, v20
	v_sub_f32_e32 v67, v68, v70
	v_lshlrev_b32_e32 v71, 16, v69
	v_mul_f32_e32 v67, v67, v62
	v_sub_f32_e32 v66, v66, v70
	v_and_b32_e32 v69, 0xffff0000, v69
	v_fma_f32 v68, v17, v67, v21
	v_sub_f32_e32 v67, v71, v70
	v_mul_f32_e32 v66, v66, v62
	v_sub_f32_e32 v63, v63, v70
	v_sub_f32_e32 v64, v64, v70
	v_sub_f32_e32 v65, v65, v70
	v_mul_f32_e32 v67, v67, v62
	v_fma_f32 v75, v31, v66, v27
	v_sub_f32_e32 v66, v69, v70
	v_mul_f32_e32 v63, v63, v62
	v_mul_f32_e32 v64, v64, v62
	v_mul_f32_e32 v65, v65, v62
	v_fma_f32 v71, v18, v67, v22
	v_mul_f32_e32 v62, v66, v62
	v_pk_mul_f32 v[66:67], v[72:73], s[46:47] op_sel_hi:[1,0]
	v_fma_f32 v64, v29, v64, v25
	v_fma_f32 v67, -v66, v66, v67
	v_max_f32_e32 v67, 0, v67
	v_add_f32_e32 v67, 0x358637bd, v67
	v_mul_f32_e32 v69, 0x4f800000, v67
	v_cmp_gt_f32_e32 vcc, s61, v67
	v_fma_f32 v63, v28, v63, v24
	v_fma_f32 v65, v30, v65, v26
	v_cndmask_b32_e32 v67, v67, v69, vcc
	v_sqrt_f32_e32 v69, v67
	v_fma_f32 v70, v19, v62, v23
	v_cvt_pk_bf16_f32 v62, v63, v64
	v_cvt_pk_bf16_f32 v63, v65, v75
	v_add_u32_e32 v64, -1, v69
	v_fma_f32 v65, -v64, v69, v67
	v_cmp_ge_f32_e64 s[2:3], 0, v65
	v_add_u32_e32 v65, 1, v69
	s_nop 0
	v_cndmask_b32_e64 v64, v69, v64, s[2:3]
	v_fma_f32 v69, -v65, v69, v67
	v_cmp_lt_f32_e64 s[2:3], 0, v69
	s_nop 1
	v_cndmask_b32_e64 v64, v64, v65, s[2:3]
	v_mul_f32_e32 v65, 0x37800000, v64
	v_cndmask_b32_e32 v64, v64, v65, vcc
	v_cmp_class_f32_e32 vcc, v67, v166
	s_nop 1
	v_cndmask_b32_e32 v67, v64, v67, vcc
	v_div_scale_f32 v69, s[0:1], v67, v67, 1.0
	v_rcp_f32_e32 v72, v69
	v_cvt_pk_bf16_f32 v64, v74, v68
	v_cvt_pk_bf16_f32 v65, v71, v70
	ds_write_b128 v76, v[62:65] offset:9216
	v_fma_f32 v62, -v69, v72, 1.0
	v_fmac_f32_e32 v72, v62, v72
	v_div_scale_f32 v62, vcc, 1.0, v67, 1.0
	v_mul_f32_e32 v63, v62, v72
	v_fma_f32 v64, -v69, v63, v62
	v_fmac_f32_e32 v63, v64, v72
	v_fma_f32 v62, -v69, v63, v62
	v_div_fmas_f32 v62, v62, v72, v63
	v_div_fixup_f32 v62, v62, v67, 1.0
	v_lshlrev_b32_e32 v63, 16, v36
	v_and_b32_e32 v36, 0xffff0000, v36
	v_lshlrev_b32_e32 v64, 16, v37
	v_and_b32_e32 v37, 0xffff0000, v37
	v_lshlrev_b32_e32 v65, 16, v38
	v_and_b32_e32 v38, 0xffff0000, v38
	v_lshlrev_b32_e32 v67, 16, v39
	v_and_b32_e32 v39, 0xffff0000, v39
	v_sub_f32_e32 v63, v63, v66
	v_sub_f32_e32 v65, v65, v66
	v_sub_f32_e32 v36, v36, v66
	v_sub_f32_e32 v38, v38, v66
	v_sub_f32_e32 v64, v64, v66
	v_sub_f32_e32 v67, v67, v66
	v_sub_f32_e32 v37, v37, v66
	v_sub_f32_e32 v39, v39, v66
	v_mul_f32_e32 v63, v63, v62
	v_mul_f32_e32 v65, v65, v62
	v_mul_f32_e32 v36, v36, v62
	v_mul_f32_e32 v38, v38, v62
	v_mul_f32_e32 v64, v64, v62
	v_mul_f32_e32 v67, v67, v62
	v_mul_f32_e32 v37, v37, v62
	v_mul_f32_e32 v39, v39, v62
	v_mul_f32_e32 v62, 0x4f800000, v59
	v_cmp_gt_f32_e32 vcc, s61, v59
	v_fma_f32 v63, v28, v63, v24
	v_fma_f32 v36, v29, v36, v25
	v_cndmask_b32_e32 v59, v59, v62, vcc
	v_sqrt_f32_e32 v62, v59
	v_fma_f32 v64, v30, v64, v26
	v_fma_f32 v37, v31, v37, v27
	v_cvt_pk_bf16_f32 v36, v63, v36
	v_add_u32_e32 v63, -1, v62
	v_cvt_pk_bf16_f32 v37, v64, v37
	v_fma_f32 v64, -v63, v62, v59
	v_cmp_ge_f32_e64 s[2:3], 0, v64
	v_add_u32_e32 v64, 1, v62
	v_fma_f32 v38, v17, v38, v21
	v_cndmask_b32_e64 v63, v62, v63, s[2:3]
	v_fma_f32 v62, -v64, v62, v59
	v_cmp_lt_f32_e64 s[2:3], 0, v62
	v_fma_f32 v39, v19, v39, v23
	v_fma_f32 v65, v16, v65, v20
	v_cndmask_b32_e64 v62, v63, v64, s[2:3]
	v_mul_f32_e32 v63, 0x37800000, v62
	v_cndmask_b32_e32 v62, v62, v63, vcc
	v_cmp_class_f32_e32 vcc, v59, v166
	v_fma_f32 v67, v18, v67, v22
	v_cvt_pk_bf16_f32 v38, v65, v38
	v_cvt_pk_bf16_f32 v39, v67, v39
	ds_write_b128 v76, v[36:39] offset:18432
	v_cndmask_b32_e32 v59, v62, v59, vcc
	v_div_scale_f32 v62, s[0:1], v59, v59, 1.0
	v_rcp_f32_e32 v63, v62
	v_lshlrev_b32_e32 v39, 16, v34
	v_and_b32_e32 v34, 0xffff0000, v34
	v_fma_f32 v36, -v62, v63, 1.0
	v_fmac_f32_e32 v63, v36, v63
	v_div_scale_f32 v36, vcc, 1.0, v59, 1.0
	v_mul_f32_e32 v37, v36, v63
	v_fma_f32 v38, -v62, v37, v36
	v_fmac_f32_e32 v37, v38, v63
	v_fma_f32 v36, -v62, v37, v36
	v_div_fmas_f32 v36, v36, v63, v37
	v_lshlrev_b32_e32 v37, 16, v32
	v_div_fixup_f32 v36, v36, v59, 1.0
	v_sub_f32_e32 v37, v37, v58
	v_mul_f32_e32 v37, v37, v36
	v_fma_f32 v24, v28, v37, v24
	v_sub_f32_e32 v28, v39, v58
	v_and_b32_e32 v32, 0xffff0000, v32
	v_mul_f32_e32 v28, v28, v36
	v_fma_f32 v20, v16, v28, v20
	v_sub_f32_e32 v16, v32, v58
	v_mul_f32_e32 v16, v16, v36
	v_fma_f32 v16, v29, v16, v25
	v_sub_f32_e32 v25, v34, v58
	v_lshlrev_b32_e32 v59, 16, v35
	v_mul_f32_e32 v25, v25, v36
	v_fma_f32 v21, v17, v25, v21
	v_sub_f32_e32 v25, v59, v58
	v_lshlrev_b32_e32 v38, 16, v33
	v_and_b32_e32 v33, 0xffff0000, v33
	v_mul_f32_e32 v25, v25, v36
	v_fma_f32 v22, v18, v25, v22
	v_sub_f32_e32 v18, v33, v58
	v_and_b32_e32 v35, 0xffff0000, v35
	v_sub_f32_e32 v17, v38, v58
	v_mul_f32_e32 v18, v18, v36
	v_mul_f32_e32 v17, v17, v36
	v_fmac_f32_e32 v27, v31, v18
	v_sub_f32_e32 v18, v35, v58
	v_fma_f32 v17, v30, v17, v26
	v_mul_f32_e32 v18, v18, v36
	v_cvt_pk_bf16_f32 v16, v24, v16
	v_fmac_f32_e32 v23, v19, v18
	v_cvt_pk_bf16_f32 v17, v17, v27
	v_cvt_pk_bf16_f32 v18, v20, v21
	v_cvt_pk_bf16_f32 v19, v22, v23
	ds_write_b128 v76, v[16:19] offset:27648
	v_bfe_u32 v16, v41, 2, 2
	v_or_b32_e32 v16, v162, v16
	v_and_b32_e32 v17, 24, v77
	v_mul_u32_u24_e32 v16, 0x120, v16
	v_add3_u32 v41, 0, v17, v16
	s_waitcnt lgkmcnt(0)
	s_barrier
; #define LAS __attribute__((address_space(3)))
; __device__ __forceinline__ void gmlp_unit(const bf16* proj, unsigned char* ws, LAS unsigned char* lds, int gu) {
;     ...
;     f32x4 acc[8];
; #pragma unroll
;     for (int ct = 0; ct < 8; ++ct) {
;         acc[ct] = (f32x4){0.f, 0.f, 0.f, 0.f};
; #pragma unroll
;         for (int s = 0; s < 4; ++s) {
;             const LAS unsigned char* p0 = VN + (32 * s + 8 * fq + (fr >> 2)) * V_STRIDE + (16 * ct + 4 * (fr & 3)) * 2;
;             const bf16x8 vf = tr_frag(p0, p0 + 4 * V_STRIDE);
;             acc[ct] = __builtin_amdgcn_mfma_f32_16x16x32_bf16(vf, wf[s], acc[ct], 0, 0, 0);
;         }
;     }
	v_mov_b32_e32 v252, v41
	ds_read_b64_tr_b16 v[110:111], v252 offset:32
	ds_read_b64_tr_b16 v[112:113], v252 offset:1184
	ds_read_b64_tr_b16 v[114:115], v252
	ds_read_b64_tr_b16 v[116:117], v252 offset:1152
	ds_read_b64_tr_b16 v[118:119], v252 offset:9248
	ds_read_b64_tr_b16 v[120:121], v252 offset:10400
	ds_read_b64_tr_b16 v[122:123], v252 offset:9216
	ds_read_b64_tr_b16 v[124:125], v252 offset:10368
	ds_read_b64_tr_b16 v[126:127], v252 offset:18464
	ds_read_b64_tr_b16 v[128:129], v252 offset:19616
	ds_read_b64_tr_b16 v[130:131], v252 offset:18432
	ds_read_b64_tr_b16 v[132:133], v252 offset:19584
	s_waitcnt vmcnt(3)
	s_waitcnt lgkmcnt(10)
	v_mfma_f32_16x16x32_bf16 v[24:27], v[110:113], v[0:3], 0
	ds_read_b64_tr_b16 v[134:135], v252 offset:27680
	ds_read_b64_tr_b16 v[136:137], v252 offset:28832
	s_waitcnt lgkmcnt(10)
	v_mfma_f32_16x16x32_bf16 v[16:19], v[114:117], v[0:3], 0
	ds_read_b64_tr_b16 v[138:139], v252 offset:64
	ds_read_b64_tr_b16 v[140:141], v252 offset:1216
	s_waitcnt vmcnt(2)
	s_waitcnt lgkmcnt(10)
	v_mfma_f32_16x16x32_bf16 v[24:27], v[118:121], v[4:7], v[24:27]
	ds_read_b64_tr_b16 v[142:143], v252 offset:96
	ds_read_b64_tr_b16 v[144:145], v252 offset:1248
	s_waitcnt lgkmcnt(10)
	v_mfma_f32_16x16x32_bf16 v[16:19], v[122:125], v[4:7], v[16:19]
	ds_read_b64_tr_b16 v[146:147], v252 offset:27648
	ds_read_b64_tr_b16 v[148:149], v252 offset:28800
	s_waitcnt vmcnt(1)
	s_waitcnt lgkmcnt(10)
	v_mfma_f32_16x16x32_bf16 v[24:27], v[126:129], v[12:15], v[24:27]
	ds_read_b64_tr_b16 v[150:151], v252 offset:9280
	ds_read_b64_tr_b16 v[152:153], v252 offset:10432
	s_waitcnt lgkmcnt(10)
	v_mfma_f32_16x16x32_bf16 v[16:19], v[130:133], v[12:15], v[16:19]
	ds_read_b64_tr_b16 v[154:155], v252 offset:9312
	ds_read_b64_tr_b16 v[156:157], v252 offset:10464
	s_waitcnt vmcnt(0)
	s_waitcnt lgkmcnt(10)
	v_mfma_f32_16x16x32_bf16 v[20:23], v[134:137], v[8:11], v[24:27]
	ds_read_b64_tr_b16 v[172:173], v252 offset:160
	ds_read_b64_tr_b16 v[174:175], v252 offset:1312
	s_waitcnt lgkmcnt(10)
	v_mfma_f32_16x16x32_bf16 v[24:27], v[138:141], v[0:3], 0
	ds_read_b64_tr_b16 v[176:177], v252 offset:18496
	ds_read_b64_tr_b16 v[178:179], v252 offset:19648
	s_waitcnt lgkmcnt(10)
	v_mfma_f32_16x16x32_bf16 v[28:31], v[142:145], v[0:3], 0
	ds_read_b64_tr_b16 v[180:181], v252 offset:18528
	ds_read_b64_tr_b16 v[182:183], v252 offset:19680
	s_waitcnt lgkmcnt(10)
	v_mfma_f32_16x16x32_bf16 v[16:19], v[146:149], v[8:11], v[16:19]
	ds_read_b64_tr_b16 v[184:185], v252 offset:128
	ds_read_b64_tr_b16 v[186:187], v252 offset:1280
	s_waitcnt lgkmcnt(10)
	v_mfma_f32_16x16x32_bf16 v[24:27], v[150:153], v[4:7], v[24:27]
	ds_read_b64_tr_b16 v[188:189], v252 offset:9376
	ds_read_b64_tr_b16 v[190:191], v252 offset:10528
	s_waitcnt lgkmcnt(10)
	v_mfma_f32_16x16x32_bf16 v[28:31], v[154:157], v[4:7], v[28:31]
	ds_read_b64_tr_b16 v[192:193], v252 offset:27712
	ds_read_b64_tr_b16 v[194:195], v252 offset:28864
	s_waitcnt lgkmcnt(10)
	v_mfma_f32_16x16x32_bf16 v[62:65], v[172:175], v[0:3], 0
	ds_read_b64_tr_b16 v[196:197], v252 offset:27744
	ds_read_b64_tr_b16 v[198:199], v252 offset:28896
	s_waitcnt lgkmcnt(10)
	v_mfma_f32_16x16x32_bf16 v[24:27], v[176:179], v[12:15], v[24:27]
	ds_read_b64_tr_b16 v[200:201], v252 offset:9344
	ds_read_b64_tr_b16 v[202:203], v252 offset:10496
	s_waitcnt lgkmcnt(10)
	v_mfma_f32_16x16x32_bf16 v[28:31], v[180:183], v[12:15], v[28:31]
	ds_read_b64_tr_b16 v[204:205], v252 offset:18592
	ds_read_b64_tr_b16 v[206:207], v252 offset:19744
	s_waitcnt lgkmcnt(10)
	v_mfma_f32_16x16x32_bf16 v[32:35], v[184:187], v[0:3], 0
	ds_read_b64_tr_b16 v[208:209], v252 offset:18560
	ds_read_b64_tr_b16 v[210:211], v252 offset:19712
	s_waitcnt lgkmcnt(10)
	v_mfma_f32_16x16x32_bf16 v[62:65], v[188:191], v[4:7], v[62:65]
	ds_read_b64_tr_b16 v[212:213], v252 offset:27808
	ds_read_b64_tr_b16 v[214:215], v252 offset:28960
	s_waitcnt lgkmcnt(10)
	v_mfma_f32_16x16x32_bf16 v[24:27], v[192:195], v[8:11], v[24:27]
	ds_read_b64_tr_b16 v[216:217], v252 offset:192
	ds_read_b64_tr_b16 v[218:219], v252 offset:1344
	s_waitcnt lgkmcnt(10)
	v_mfma_f32_16x16x32_bf16 v[28:31], v[196:199], v[8:11], v[28:31]
	ds_read_b64_tr_b16 v[220:221], v252 offset:224
	ds_read_b64_tr_b16 v[222:223], v252 offset:1376
	s_waitcnt lgkmcnt(10)
	v_mfma_f32_16x16x32_bf16 v[32:35], v[200:203], v[4:7], v[32:35]
	ds_read_b64_tr_b16 v[224:225], v252 offset:9408
	ds_read_b64_tr_b16 v[226:227], v252 offset:10560
	s_waitcnt lgkmcnt(10)
	v_mfma_f32_16x16x32_bf16 v[62:65], v[204:207], v[12:15], v[62:65]
	ds_read_b64_tr_b16 v[228:229], v252 offset:9440
	ds_read_b64_tr_b16 v[230:231], v252 offset:10592
	s_waitcnt lgkmcnt(10)
	v_mfma_f32_16x16x32_bf16 v[32:35], v[208:211], v[12:15], v[32:35]
	ds_read_b64_tr_b16 v[232:233], v252 offset:18624
	ds_read_b64_tr_b16 v[234:235], v252 offset:19776
	v_ashrrev_i32_e32 v41, 31, v40
	s_waitcnt lgkmcnt(10)
	v_mfma_f32_16x16x32_bf16 v[36:39], v[212:215], v[8:11], v[62:65]
	ds_read_b64_tr_b16 v[236:237], v252 offset:18656
	ds_read_b64_tr_b16 v[238:239], v252 offset:19808
	s_waitcnt lgkmcnt(10)
	v_mfma_f32_16x16x32_bf16 v[62:65], v[216:219], v[0:3], 0
	ds_read_b64_tr_b16 v[240:241], v252 offset:27776
	ds_read_b64_tr_b16 v[242:243], v252 offset:28928
	s_waitcnt lgkmcnt(10)
	v_mfma_f32_16x16x32_bf16 v[0:3], v[220:223], v[0:3], 0
	ds_read_b64_tr_b16 v[244:245], v252 offset:27840
	ds_read_b64_tr_b16 v[246:247], v252 offset:28992
	s_waitcnt lgkmcnt(10)
	v_mfma_f32_16x16x32_bf16 v[62:65], v[224:227], v[4:7], v[62:65]
	ds_read_b64_tr_b16 v[248:249], v252 offset:27872
	ds_read_b64_tr_b16 v[250:251], v252 offset:29024
	s_waitcnt lgkmcnt(10)
; #define LAS __attribute__((address_space(3)))
; __device__ __forceinline__ unsigned pk2(float lo, float hi) { return pg8::cvt_pk_bf16(lo, hi); }
; __device__ __forceinline__ void gmlp_unit(const bf16* proj, unsigned char* ws, LAS unsigned char* lds, int gu) {
;     ...
; #pragma unroll
;     for (int ct = 0; ct < 8; ++ct) {
;         acc[ct] = (f32x4){0.f, 0.f, 0.f, 0.f};
; #pragma unroll
;         for (int s = 0; s < 4; ++s) {
;             const LAS unsigned char* p0 = VN + (32 * s + 8 * fq + (fr >> 2)) * V_STRIDE + (16 * ct + 4 * (fr & 3)) * 2;
;             const bf16x8 vf = tr_frag(p0, p0 + 4 * V_STRIDE);
;             acc[ct] = __builtin_amdgcn_mfma_f32_16x16x32_bf16(vf, wf[s], acc[ct], 0, 0, 0);
;         }
;     }
;     float ss = 0.f;
; #pragma unroll
;     for (int ct = 0; ct < 8; ++ct) {
;         const float o0 = bflo(uw[ct].x) * (acc[ct][0] + bsp), o1 = bfhi(uw[ct].x) * (acc[ct][1] + bsp), o2 = bflo(uw[ct].y) * (acc[ct][2] + bsp), o3 = bfhi(uw[ct].y) * (acc[ct][3] + bsp);
;         ss += (o0 * o0 + o1 * o1) + (o2 * o2 + o3 * o3);
;         v2u w; w.x = pk2(o0, o1); w.y = pk2(o2, o3); *(v2u*)(orow + 16 * ct) = w;
;     }
;     ss += __shfl_xor(ss, 16); ss += __shfl_xor(ss, 32);
;     if (fq == 0) unsafeAtomicAdd(ssmix + (size_t)tok * 2 + 1, ss);
	v_mfma_f32_16x16x32_bf16 v[0:3], v[228:231], v[4:7], v[0:3]
	v_lshlrev_b64 v[4:5], 12, v[40:41]
	v_lshl_add_u64 v[4:5], s[28:29], 0, v[4:5]
	v_lshl_add_u64 v[4:5], v[4:5], 0, s[44:45]
	s_waitcnt lgkmcnt(8)
	v_mfma_f32_16x16x32_bf16 v[62:65], v[232:235], v[12:15], v[62:65]
	v_lshl_add_u64 v[4:5], v[4:5], 0, v[162:163]
	v_lshl_add_u64 v[6:7], v[4:5], 0, s[48:49]
	v_add_co_u32_e32 v4, vcc, s63, v4
	s_waitcnt lgkmcnt(6)
	v_mfma_f32_16x16x32_bf16 v[0:3], v[236:239], v[12:15], v[0:3]
	v_add_f32_e32 v12, v61, v19
	v_addc_co_u32_e32 v5, vcc, 0, v5, vcc
	s_waitcnt lgkmcnt(4)
	v_mfma_f32_16x16x32_bf16 v[32:35], v[240:243], v[8:11], v[32:35]
	v_cmp_lt_i32_e32 vcc, v168, v169
	s_waitcnt lgkmcnt(2)
	v_mfma_f32_16x16x32_bf16 v[62:65], v[244:247], v[8:11], v[62:65]
	s_waitcnt lgkmcnt(0)
	v_mfma_f32_16x16x32_bf16 v[0:3], v[248:251], v[8:11], v[0:3]
	v_lshlrev_b32_e32 v8, 16, v56
	v_add_f32_e32 v9, v61, v16
	v_mul_f32_e32 v8, v9, v8
	v_and_b32_e32 v9, 0xffff0000, v56
	v_add_f32_e32 v10, v61, v17
	v_mul_f32_e32 v9, v10, v9
	v_lshlrev_b32_e32 v10, 16, v57
	v_add_f32_e32 v11, v61, v18
	v_mul_f32_e32 v10, v11, v10
	v_and_b32_e32 v11, 0xffff0000, v57
	v_mul_f32_e32 v11, v12, v11
	v_mul_f32_e32 v12, v9, v9
	v_fmac_f32_e32 v12, v8, v8
	v_cvt_pk_bf16_f32 v8, v8, v9
	v_cvt_pk_bf16_f32 v9, v10, v11
	global_store_dwordx2 v[4:5], v[8:9], off offset:2048
	v_lshlrev_b32_e32 v4, 16, v54
	v_add_f32_e32 v5, v61, v20
	v_mul_f32_e32 v4, v5, v4
	v_and_b32_e32 v5, 0xffff0000, v54
	v_add_f32_e32 v8, v61, v21
	v_mul_f32_e32 v13, v11, v11
	v_mul_f32_e32 v5, v8, v5
	v_lshlrev_b32_e32 v8, 16, v55
	v_add_f32_e32 v9, v61, v22
	v_fmac_f32_e32 v13, v10, v10
	v_mul_f32_e32 v8, v9, v8
	v_and_b32_e32 v9, 0xffff0000, v55
	v_add_f32_e32 v10, v61, v23
	v_mul_f32_e32 v9, v10, v9
	v_mul_f32_e32 v10, v5, v5
	v_fmac_f32_e32 v10, v4, v4
	v_cvt_pk_bf16_f32 v4, v4, v5
	v_cvt_pk_bf16_f32 v5, v8, v9
	v_mul_f32_e32 v11, v9, v9
	global_store_dwordx2 v[6:7], v[4:5], off offset:32
	v_lshlrev_b32_e32 v4, 16, v52
	v_add_f32_e32 v5, v61, v24
	v_fmac_f32_e32 v11, v8, v8
	v_mul_f32_e32 v4, v5, v4
	v_and_b32_e32 v5, 0xffff0000, v52
	v_add_f32_e32 v8, v61, v25
	v_mul_f32_e32 v5, v8, v5
	v_lshlrev_b32_e32 v8, 16, v53
	v_add_f32_e32 v9, v61, v26
	v_add_f32_e32 v10, v10, v11
	v_mul_f32_e32 v8, v9, v8
	v_and_b32_e32 v9, 0xffff0000, v53
	v_add_f32_e32 v11, v61, v27
	v_mul_f32_e32 v9, v11, v9
	v_mul_f32_e32 v11, v5, v5
	v_add_f32_e32 v12, v12, v13
	v_fmac_f32_e32 v11, v4, v4
	v_cvt_pk_bf16_f32 v4, v4, v5
	v_cvt_pk_bf16_f32 v5, v8, v9
	v_add_f32_e32 v10, v12, v10
	v_mul_f32_e32 v12, v9, v9
	global_store_dwordx2 v[6:7], v[4:5], off offset:64
	v_lshlrev_b32_e32 v4, 16, v50
	v_add_f32_e32 v5, v61, v28
	v_fmac_f32_e32 v12, v8, v8
	v_mul_f32_e32 v4, v5, v4
	v_and_b32_e32 v5, 0xffff0000, v50
	v_add_f32_e32 v8, v61, v29
	v_add_f32_e32 v11, v11, v12
	v_mul_f32_e32 v5, v8, v5
	v_lshlrev_b32_e32 v8, 16, v51
	v_add_f32_e32 v9, v61, v30
	v_add_f32_e32 v10, v10, v11
	v_mul_f32_e32 v8, v9, v8
	v_and_b32_e32 v9, 0xffff0000, v51
	v_add_f32_e32 v11, v61, v31
	v_mul_f32_e32 v9, v11, v9
	v_mul_f32_e32 v11, v5, v5
	v_fmac_f32_e32 v11, v4, v4
	v_cvt_pk_bf16_f32 v4, v4, v5
	v_cvt_pk_bf16_f32 v5, v8, v9
	v_mul_f32_e32 v12, v9, v9
	global_store_dwordx2 v[6:7], v[4:5], off offset:96
	v_lshlrev_b32_e32 v4, 16, v48
	v_add_f32_e32 v5, v61, v32
	v_fmac_f32_e32 v12, v8, v8
	v_mul_f32_e32 v4, v5, v4
	v_and_b32_e32 v5, 0xffff0000, v48
	v_add_f32_e32 v8, v61, v33
	v_add_f32_e32 v11, v11, v12
	v_mul_f32_e32 v5, v8, v5
	v_lshlrev_b32_e32 v8, 16, v49
	v_add_f32_e32 v9, v61, v34
	v_add_f32_e32 v10, v10, v11
	v_mul_f32_e32 v8, v9, v8
	v_and_b32_e32 v9, 0xffff0000, v49
	v_add_f32_e32 v11, v61, v35
	v_mul_f32_e32 v9, v11, v9
	v_mul_f32_e32 v11, v5, v5
	v_fmac_f32_e32 v11, v4, v4
	v_cvt_pk_bf16_f32 v4, v4, v5
	v_cvt_pk_bf16_f32 v5, v8, v9
	v_mul_f32_e32 v12, v9, v9
	global_store_dwordx2 v[6:7], v[4:5], off offset:128
	v_lshlrev_b32_e32 v4, 16, v46
	v_add_f32_e32 v5, v61, v36
	v_fmac_f32_e32 v12, v8, v8
	v_mul_f32_e32 v4, v5, v4
	v_and_b32_e32 v5, 0xffff0000, v46
	v_add_f32_e32 v8, v61, v37
	v_add_f32_e32 v11, v11, v12
	v_mul_f32_e32 v5, v8, v5
	v_lshlrev_b32_e32 v8, 16, v47
	v_add_f32_e32 v9, v61, v38
	v_add_f32_e32 v10, v10, v11
	v_mul_f32_e32 v8, v9, v8
	v_and_b32_e32 v9, 0xffff0000, v47
	v_add_f32_e32 v11, v61, v39
	v_mul_f32_e32 v9, v11, v9
	v_mul_f32_e32 v11, v5, v5
	v_mul_f32_e32 v12, v9, v9
	v_fmac_f32_e32 v11, v4, v4
	v_fmac_f32_e32 v12, v8, v8
	v_add_f32_e32 v11, v11, v12
	v_cvt_pk_bf16_f32 v4, v4, v5
	v_cvt_pk_bf16_f32 v5, v8, v9
	v_lshlrev_b32_e32 v8, 16, v44
	v_add_f32_e32 v9, v61, v62
	v_add_f32_e32 v10, v10, v11
	v_mul_f32_e32 v8, v9, v8
	v_and_b32_e32 v9, 0xffff0000, v44
	v_add_f32_e32 v11, v61, v63
	v_mul_f32_e32 v9, v11, v9
	v_lshlrev_b32_e32 v11, 16, v45
	v_add_f32_e32 v12, v61, v64
	v_mul_f32_e32 v11, v12, v11
	v_and_b32_e32 v12, 0xffff0000, v45
	v_add_f32_e32 v13, v61, v65
	v_mul_f32_e32 v12, v13, v12
	v_mul_f32_e32 v13, v9, v9
	v_mul_f32_e32 v14, v12, v12
	v_fmac_f32_e32 v13, v8, v8
	v_fmac_f32_e32 v14, v11, v11
	v_add_f32_e32 v13, v13, v14
	v_add_f32_e32 v10, v10, v13
	v_lshlrev_b32_e32 v13, 16, v42
	v_add_f32_e32 v0, v61, v0
	v_mul_f32_e32 v13, v0, v13
	v_and_b32_e32 v0, 0xffff0000, v42
	v_add_f32_e32 v1, v61, v1
	v_mul_f32_e32 v14, v1, v0
	v_lshlrev_b32_e32 v0, 16, v43
	v_add_f32_e32 v1, v61, v2
	v_mul_f32_e32 v15, v1, v0
	v_and_b32_e32 v0, 0xffff0000, v43
	v_add_f32_e32 v1, v61, v3
	v_mul_f32_e32 v3, v1, v0
	v_mul_f32_e32 v0, v14, v14
	v_mul_f32_e32 v1, v3, v3
	v_fmac_f32_e32 v0, v13, v13
	v_fmac_f32_e32 v1, v15, v15
	v_add_f32_e32 v0, v0, v1
	v_add_f32_e32 v2, v10, v0
	v_cndmask_b32_e32 v0, v167, v168, vcc
	v_lshlrev_b32_e32 v0, 2, v0
	ds_bpermute_b32 v10, v0, v2
	global_store_dwordx2 v[6:7], v[4:5], off offset:160
	v_cvt_pk_bf16_f32 v0, v8, v9
	v_cvt_pk_bf16_f32 v1, v11, v12
	v_cmp_lt_i32_e32 vcc, v170, v169
	global_store_dwordx2 v[6:7], v[0:1], off offset:192
	s_waitcnt lgkmcnt(0)
	v_add_f32_e32 v0, v2, v10
	v_cndmask_b32_e32 v1, v167, v170, vcc
	v_lshlrev_b32_e32 v1, 2, v1
	ds_bpermute_b32 v1, v1, v0
	v_cmp_eq_u32_e32 vcc, 0, v60
	v_cvt_pk_bf16_f32 v2, v13, v14
	v_cvt_pk_bf16_f32 v3, v15, v3
	global_store_dwordx2 v[6:7], v[2:3], off offset:224
	s_and_saveexec_b64 s[2:3], vcc
	s_cbranch_execz .LBB0_602
	s_waitcnt lgkmcnt(0)
	v_add_f32_e32 v2, v0, v1
	v_lshl_add_u64 v[0:1], v[40:41], 3, s[28:29]
	v_add_co_u32_e32 v0, vcc, 0x40000, v0
	s_nop 1
	v_addc_co_u32_e32 v1, vcc, 0, v1, vcc
	global_atomic_add_f32 v[0:1], v2, off offset:4
